# c4 plus 52B s_nop pad at P5 entry restoring baseline byte alignment of P5 and P6 hot loops
# speedup vs baseline: 1.0139x; 1.0131x over previous
.LBB0_1184:
.LBB0_1185:
	s_nop 0
	s_nop 0
	s_nop 0
	s_nop 0
	s_nop 0
	s_nop 0
	s_nop 0
	s_nop 0
	s_nop 0
	s_nop 0
	s_nop 0
	s_nop 0
	s_nop 0
	s_cmp_lt_i32 s92, 6
	s_cselect_b64 s[0:1], -1, 0
	s_cmp_gt_i32 s93, 5
	s_cselect_b64 s[2:3], -1, 0
	s_and_b64 s[0:1], s[0:1], s[2:3]
	s_andn2_b64 vcc, exec, s[0:1]
	s_cbranch_vccnz .LBB0_1450
	s_andn2_b64 vcc, exec, s[8:9]
	s_cbranch_vccnz .LBB0_1194
	v_readlane_b32 s0, v254, 24
	s_cmp_gt_u32 s0, 63
	v_mbcnt_lo_u32_b32 v0, -1, 0
	v_mbcnt_hi_u32_b32 v0, -1, v0
	s_cbranch_scc1 .LBB0_1193
	v_readlane_b32 s0, v254, 0
	v_readlane_b32 s1, v254, 1
	v_readlane_b32 s2, v254, 2
	v_readlane_b32 s3, v254, 3
	v_readlane_b32 s4, v254, 4
	v_readlane_b32 s5, v254, 5
	v_readlane_b32 s6, v254, 6
	v_readlane_b32 s7, v254, 7
	s_waitcnt lgkmcnt(0)
	v_ashrrev_i32_e32 v1, 31, v0
	v_readlane_b32 s0, v254, 16
	v_lshlrev_b64 v[2:3], 2, v[0:1]
	v_readlane_b32 s14, v254, 14
	v_readlane_b32 s15, v254, 15
	v_readlane_b32 s1, v254, 17
	v_readlane_b32 s12, v254, 12
	v_lshl_add_u64 v[4:5], s[14:15], 0, v[2:3]
	v_lshl_add_u64 v[2:3], s[0:1], 0, v[2:3]
	global_load_dword v6, v[4:5], off
	global_load_dword v7, v[4:5], off offset:256
	s_nop 0
	global_load_dword v4, v[2:3], off offset:256
	global_load_dword v5, v[2:3], off
	v_mbcnt_lo_u32_b32 v2, -1, 0
	v_mbcnt_hi_u32_b32 v2, -1, v2
	v_and_b32_e32 v3, 64, v2
	v_xor_b32_e32 v8, 1, v2
	v_add_u32_e32 v3, 64, v3
	v_cmp_lt_i32_e32 vcc, v8, v3
	v_xor_b32_e32 v9, 2, v2
	v_xor_b32_e32 v10, 4, v2
	v_cndmask_b32_e32 v8, v2, v8, vcc
	v_lshlrev_b32_e32 v8, 2, v8
	v_cmp_lt_i32_e32 vcc, v9, v3
	v_xor_b32_e32 v11, 8, v2
	v_xor_b32_e32 v12, 16, v2
	v_xor_b32_e32 v13, 32, v2
	v_readlane_b32 s13, v254, 13
	v_readlane_b32 s8, v254, 8
	v_readlane_b32 s9, v254, 9
	v_readlane_b32 s10, v254, 10
	v_readlane_b32 s11, v254, 11
	v_readlane_b32 s2, v254, 18
	v_readlane_b32 s3, v254, 19
	v_readlane_b32 s4, v254, 20
	v_readlane_b32 s5, v254, 21
	v_readlane_b32 s6, v254, 22
	v_readlane_b32 s7, v254, 23
	s_waitcnt vmcnt(0)
	v_max_f32_e64 v6, |v6|, |v6|
	v_max_f32_e64 v7, |v7|, |v7|
	v_max_f32_e64 v4, |v4|, |v4|
	v_max_f32_e64 v5, |v5|, |v5|
	v_max_f32_e32 v6, v6, v7
	v_max_f32_e32 v4, v5, v4
	ds_bpermute_b32 v5, v8, v6
	ds_bpermute_b32 v7, v8, v4
	v_cndmask_b32_e32 v8, v2, v9, vcc
	v_lshlrev_b32_e32 v8, 2, v8
	v_cmp_lt_i32_e32 vcc, v10, v3
	s_waitcnt lgkmcnt(1)
	v_max_f32_e32 v5, v5, v5
	s_waitcnt lgkmcnt(0)
	v_max_f32_e32 v7, v7, v7
	v_max_f32_e32 v5, v6, v5
	v_max_f32_e32 v4, v4, v7
	ds_bpermute_b32 v6, v8, v5
	ds_bpermute_b32 v7, v8, v4
	v_cndmask_b32_e32 v8, v2, v10, vcc
	v_lshlrev_b32_e32 v8, 2, v8
	v_cmp_lt_i32_e32 vcc, v11, v3
	s_waitcnt lgkmcnt(1)
	v_max_f32_e32 v6, v6, v6
	s_waitcnt lgkmcnt(0)
	v_max_f32_e32 v7, v7, v7
	v_max_f32_e32 v5, v5, v6
	v_max_f32_e32 v4, v4, v7
	ds_bpermute_b32 v6, v8, v5
	ds_bpermute_b32 v7, v8, v4
	v_cndmask_b32_e32 v8, v2, v11, vcc
	v_lshlrev_b32_e32 v8, 2, v8
	v_cmp_lt_i32_e32 vcc, v12, v3
	s_waitcnt lgkmcnt(1)
	v_max_f32_e32 v6, v6, v6
	s_waitcnt lgkmcnt(0)
	v_max_f32_e32 v7, v7, v7
	v_max_f32_e32 v5, v5, v6
	v_max_f32_e32 v4, v4, v7
	ds_bpermute_b32 v6, v8, v5
	ds_bpermute_b32 v7, v8, v4
	v_cndmask_b32_e32 v8, v2, v12, vcc
	v_lshlrev_b32_e32 v8, 2, v8
	v_cmp_lt_i32_e32 vcc, v13, v3
	s_waitcnt lgkmcnt(1)
	v_max_f32_e32 v6, v6, v6
	s_waitcnt lgkmcnt(0)
	v_max_f32_e32 v7, v7, v7
	v_max_f32_e32 v5, v5, v6
	v_max_f32_e32 v4, v4, v7
	ds_bpermute_b32 v6, v8, v5
	ds_bpermute_b32 v7, v8, v4
	v_cndmask_b32_e32 v2, v2, v13, vcc
	v_lshlrev_b32_e32 v8, 2, v2
	v_cmp_gt_i32_e32 vcc, 16, v0
	s_waitcnt lgkmcnt(1)
	v_max_f32_e32 v2, v6, v6
	s_waitcnt lgkmcnt(0)
	v_max_f32_e32 v6, v7, v7
	v_max_f32_e32 v3, v5, v2
	v_max_f32_e32 v2, v4, v6
	ds_bpermute_b32 v5, v8, v3
	ds_bpermute_b32 v4, v8, v2
	s_and_saveexec_b64 s[78:79], vcc
	s_cbranch_execz .LBB0_1190
	v_lshl_add_u64 v[22:23], v[0:1], 2, s[12:13]
	v_mov_b32_e32 v24, 0
	global_load_dword v1, v[22:23], off
	global_load_dwordx4 v[6:9], v24, s[12:13]
	global_load_dwordx4 v[10:13], v24, s[12:13] offset:16
	global_load_dwordx4 v[14:17], v24, s[12:13] offset:32
	global_load_dwordx4 v[18:21], v24, s[12:13] offset:48
	v_cmp_lt_i32_e64 s[0:1], 1, v0
	v_cmp_lt_i32_e64 s[2:3], 2, v0
	v_cmp_lt_i32_e64 s[4:5], 3, v0
	v_cmp_lt_i32_e64 s[6:7], 4, v0
	v_cmp_lt_i32_e64 s[8:9], 5, v0
	v_cmp_lt_i32_e64 s[10:11], 6, v0
	v_cmp_lt_i32_e64 s[12:13], 7, v0
	v_cmp_lt_i32_e64 s[14:15], 8, v0
	v_cmp_lt_i32_e64 s[16:17], 9, v0
	v_cmp_lt_i32_e64 s[18:19], 10, v0
	v_cmp_lt_i32_e64 s[20:21], 11, v0
	v_cmp_lt_i32_e64 s[22:23], 12, v0
	v_cmp_lt_i32_e32 vcc, 0, v0
	s_waitcnt vmcnt(3)
	v_cmp_eq_f32_e64 s[30:31], v7, v1
	v_cmp_lt_f32_e64 s[28:29], v7, v1
	v_cmp_eq_f32_e64 s[36:37], v8, v1
	s_and_b64 s[0:1], s[0:1], s[30:31]
	v_cmp_lt_f32_e64 s[34:35], v8, v1
	v_cmp_eq_f32_e64 s[40:41], v9, v1
	s_and_b64 s[2:3], s[2:3], s[36:37]
	s_or_b64 s[0:1], s[28:29], s[0:1]
	v_cmp_lt_f32_e64 s[38:39], v9, v1
	s_waitcnt vmcnt(2)
	v_cmp_eq_f32_e64 s[44:45], v10, v1
	s_and_b64 s[4:5], s[4:5], s[40:41]
	v_cndmask_b32_e64 v7, 0, 1, s[0:1]
	s_or_b64 s[0:1], s[34:35], s[2:3]
	v_cmp_lt_f32_e64 s[42:43], v10, v1
	v_cmp_eq_f32_e64 s[48:49], v11, v1
	s_and_b64 s[6:7], s[6:7], s[44:45]
	v_cndmask_b32_e64 v8, 0, 1, s[0:1]
	s_or_b64 s[0:1], s[38:39], s[4:5]
	v_cmp_lt_f32_e64 s[46:47], v11, v1
	v_cmp_eq_f32_e64 s[52:53], v12, v1
	s_and_b64 s[8:9], s[8:9], s[48:49]
	v_cndmask_b32_e64 v9, 0, 1, s[0:1]
	s_or_b64 s[0:1], s[42:43], s[6:7]
	v_cmp_lt_f32_e64 s[50:51], v12, v1
	v_cmp_eq_f32_e64 s[56:57], v13, v1
	s_and_b64 s[10:11], s[10:11], s[52:53]
	v_cndmask_b32_e64 v10, 0, 1, s[0:1]
	s_or_b64 s[0:1], s[46:47], s[8:9]
	v_cmp_lt_f32_e64 s[54:55], v13, v1
	s_waitcnt vmcnt(1)
	v_cmp_eq_f32_e64 s[60:61], v14, v1
	s_and_b64 s[12:13], s[12:13], s[56:57]
	v_cndmask_b32_e64 v11, 0, 1, s[0:1]
	s_or_b64 s[0:1], s[50:51], s[10:11]
	v_cmp_lt_f32_e64 s[58:59], v14, v1
	v_cmp_eq_f32_e64 s[64:65], v15, v1
	s_and_b64 s[14:15], s[14:15], s[60:61]
	v_cndmask_b32_e64 v12, 0, 1, s[0:1]
	s_or_b64 s[0:1], s[54:55], s[12:13]
	v_cmp_lt_f32_e64 s[62:63], v15, v1
	v_cmp_eq_f32_e64 s[68:69], v16, v1
	s_and_b64 s[16:17], s[16:17], s[64:65]
	v_cndmask_b32_e64 v13, 0, 1, s[0:1]
	s_or_b64 s[0:1], s[58:59], s[14:15]
	v_cmp_lt_f32_e64 s[66:67], v16, v1
	v_cmp_eq_f32_e64 s[72:73], v17, v1
	s_and_b64 s[18:19], s[18:19], s[68:69]
	v_cndmask_b32_e64 v14, 0, 1, s[0:1]
	s_or_b64 s[0:1], s[62:63], s[16:17]
	v_cmp_lt_f32_e64 s[70:71], v17, v1
	s_waitcnt vmcnt(0)
	v_cmp_eq_f32_e64 s[76:77], v18, v1
	s_and_b64 s[20:21], s[20:21], s[72:73]
	v_cndmask_b32_e64 v15, 0, 1, s[0:1]
	s_or_b64 s[0:1], s[66:67], s[18:19]
	v_cmp_lt_f32_e64 s[74:75], v18, v1
	s_and_b64 s[22:23], s[22:23], s[76:77]
	v_cndmask_b32_e64 v16, 0, 1, s[0:1]
	s_or_b64 s[0:1], s[70:71], s[20:21]
	v_cndmask_b32_e64 v17, 0, 1, s[0:1]
	s_or_b64 s[0:1], s[74:75], s[22:23]
	v_cmp_eq_f32_e64 s[26:27], v6, v1
	v_cndmask_b32_e64 v18, 0, 1, s[0:1]
	v_cmp_eq_f32_e64 s[0:1], v19, v1
	v_cmp_lt_i32_e64 s[2:3], 13, v0
	s_and_b64 s[26:27], vcc, s[26:27]
	v_cmp_lt_f32_e32 vcc, v19, v1
	s_and_b64 s[0:1], s[2:3], s[0:1]
	s_or_b64 s[0:1], vcc, s[0:1]
	v_cmp_lt_f32_e64 s[24:25], v6, v1
	v_cndmask_b32_e64 v19, 0, 1, s[0:1]
	v_cmp_eq_f32_e64 s[0:1], v20, v1
	v_cmp_eq_u32_e64 s[2:3], 15, v0
	s_or_b64 s[24:25], s[24:25], s[26:27]
	v_cmp_lt_f32_e32 vcc, v20, v1
	s_and_b64 s[0:1], s[2:3], s[0:1]
	v_cndmask_b32_e64 v6, 0, 1, s[24:25]
	s_or_b64 s[0:1], vcc, s[0:1]
	v_cndmask_b32_e64 v20, 0, 1, s[0:1]
	v_lshlrev_b32_e32 v6, 2, v6
	s_add_i32 s0, 0, 0x12c40
	v_lshlrev_b32_e32 v7, 2, v7
	v_add3_u32 v6, s0, v6, v7
	v_lshlrev_b32_e32 v7, 2, v8
	v_lshlrev_b32_e32 v8, 2, v9
	v_add3_u32 v6, v6, v7, v8
	v_lshlrev_b32_e32 v7, 2, v10
	v_lshlrev_b32_e32 v8, 2, v11
	v_add3_u32 v6, v6, v7, v8
	v_lshlrev_b32_e32 v7, 2, v12
	v_lshlrev_b32_e32 v8, 2, v13
	v_add3_u32 v6, v6, v7, v8
	v_lshlrev_b32_e32 v7, 2, v14
	v_lshlrev_b32_e32 v8, 2, v15
	v_cmp_lt_f32_e32 vcc, v21, v1
	v_add3_u32 v6, v6, v7, v8
	v_lshlrev_b32_e32 v7, 2, v16
	v_lshlrev_b32_e32 v8, 2, v17
	v_cndmask_b32_e64 v1, 0, 1, vcc
	v_add3_u32 v6, v6, v7, v8
	v_lshlrev_b32_e32 v7, 2, v18
	v_lshlrev_b32_e32 v8, 2, v19
	v_add3_u32 v6, v6, v7, v8
	v_lshlrev_b32_e32 v7, 2, v20
	v_lshlrev_b32_e32 v1, 2, v1
	v_readlane_b32 s68, v254, 29
	v_readlane_b32 s69, v254, 28
	v_add3_u32 v1, v6, v7, v1
	ds_write_b32 v1, v0
